# baseline (speedup 1.0000x reference)
; #define SCAN_LOAD(R, TOKP) do { const float* _p = (TOKP); \
;     R##nk = *(const f32x4*)(_p + opoff); R##w = *(const f32x4*)(_p + 64 + opoff); R##b = *(const f32x4*)(_p + 128 + opoff); \
;     R##k = *(const f32x4*)(_p + 192 + opoff); R##r = *(const f32x4*)(_p + 256 + opoff); R##v = _p[voff]; } while (0)
; __device__ __forceinline__ void scan_block(const int WV, const Params& P, int layer, int bh, int hv) {
;     ...
;   auto issue = [&](int chunk) {
;     size_t t = tbase + (size_t)chunk * SCH + htok;
;     const u16* zr = z + t * DIN + hch;
;     size_t ri = t * 1024 + hch;
;     Lr = *(const unsigned*)zr; Lk = *(const unsigned*)(zr + 1024); Lv = z[t * DIN + 2048 + hrow];
;     Lw = *(const unsigned*)(rwW + ri); Lkk = *(const unsigned*)(rwKK + ri); Lb = *(const unsigned*)(rwB + ri);
;     Lgn = rwG[t * 1024 + hrow];
;   };
;     ...
;   for (int chunk = 0; chunk < NCH; ++chunk) {
;     const int buf = chunk & 1;
;     if (chunk + 1 < NCH) { commit(buf ^ 1); Lg1 = Lgn; }
;     if (chunk + 2 < NCH) {
;       if (!prep_all_done && ((chunk + 2) >> 1) >= next_check) {
;         if (__hip_atomic_load((const gu32*)pdone_s, __ATOMIC_RELAXED, __HIP_MEMORY_SCOPE_AGENT) >= gridDim.x - 64) {
;           __builtin_amdgcn_fence(__ATOMIC_ACQUIRE, "agent");
;           prep_all_done = true;
;         } else {
;           const int t0w = (chunk + 2) >> 1;
;           wait_flags16(tflag + t0w, min(64, 512 - t0w), lane);
;           next_check = t0w + 64;
;         }
;       }
;       issue(chunk + 2);
;     }
;     if (chunk >= 1) prefetch_partner(chunk - 1);
;     {
;       const float* base = ring + (size_t)buf * SCH * 384;
;       float* yb = ypart + (size_t)buf * (SCH * 512) + yoff;
;       f32x4 Ank, Aw, Ab, Ak, Ar, Bnk, Bw, Bb, Bk, Br; float Av, Bv;
;       SCAN_LOAD(A, base);
; #pragma unroll 2
;       for (int tok = 0; tok < SCH; tok += 2) {
;         SCAN_LOAD(B, base + (tok + 1) * 384);
;         SCAN_STEP(A, yb + tok * 512);
;         SCAN_LOAD(A, base + ((tok + 2) & (SCH - 1)) * 384);
;         SCAN_STEP(B, yb + (tok + 1) * 512);
;       }
.LBB0_297:
	ds_read_b128 v[76:79], v74
	ds_read_b128 v[80:83], v74 offset:256
	ds_read_b128 v[84:87], v74 offset:512
	ds_read_b128 v[88:91], v74 offset:768
	ds_read_b128 v[92:95], v74 offset:1024
	ds_read_b32 v96, v73
	s_waitcnt lgkmcnt(6)
	v_pk_mul_f32 v[98:99], v[60:61], v[2:3]
	v_pk_fma_f32 v[98:99], v[62:63], v[4:5], v[98:99]
	v_pk_mul_f32 v[100:101], v[60:61], v[6:7]
	v_add_f32_e32 v98, v98, v99
	v_pk_mul_f32 v[208:209], v[62:63], v[8:9]
	v_pk_fma_f32 v[100:101], v[210:211], v[14:15], v[100:101] op_sel_hi:[0,1,1]
	v_add_f32_dpp v98, v98, v98 row_ror:8 row_mask:0xf bank_mask:0xf
	v_pk_fma_f32 v[208:209], v[210:211], v[16:17], v[208:209] op_sel_hi:[0,1,1]
	ds_read_b128 v[212:215], v74 offset:1536
	v_add_f32_dpp v98, v98, v98 row_ror:4 row_mask:0xf bank_mask:0xf
	ds_read_b128 v[216:219], v74 offset:1792
	ds_read_b128 v[220:223], v74 offset:2048
	v_add_f32_dpp v98, v98, v98 row_ror:2 row_mask:0xf bank_mask:0xf
	ds_read_b128 v[224:227], v74 offset:2304
	ds_read_b128 v[228:231], v74 offset:2560
	v_add_f32_dpp v98, v98, v98 row_ror:1 row_mask:0xf bank_mask:0xf
	v_pk_fma_f32 v[60:61], v[98:99], v[10:11], v[100:101] op_sel_hi:[0,1,1]
	v_pk_fma_f32 v[62:63], v[98:99], v[12:13], v[208:209] op_sel_hi:[0,1,1]
	ds_read_b32 v232, v73 offset:1536
	v_pk_mul_f32 v[100:101], v[60:61], v[18:19]
	v_pk_fma_f32 v[100:101], v[62:63], v[20:21], v[100:101]
	s_nop 0
	v_add_f32_e32 v102, v100, v101
	ds_write_b32 v72, v102
	s_waitcnt lgkmcnt(7)
	v_pk_mul_f32 v[98:99], v[60:61], v[76:77]
	v_pk_fma_f32 v[98:99], v[62:63], v[78:79], v[98:99]
	v_pk_mul_f32 v[100:101], v[60:61], v[80:81]
	v_add_f32_e32 v98, v98, v99
	v_pk_mul_f32 v[208:209], v[62:63], v[82:83]
	v_pk_fma_f32 v[100:101], v[96:97], v[88:89], v[100:101] op_sel_hi:[0,1,1]
	v_add_f32_dpp v98, v98, v98 row_ror:8 row_mask:0xf bank_mask:0xf
	v_pk_fma_f32 v[208:209], v[96:97], v[90:91], v[208:209] op_sel_hi:[0,1,1]
	ds_read_b128 v[2:5], v74 offset:3072
	v_add_f32_dpp v98, v98, v98 row_ror:4 row_mask:0xf bank_mask:0xf
	ds_read_b128 v[6:9], v74 offset:3328
	ds_read_b128 v[10:13], v74 offset:3584
	v_add_f32_dpp v98, v98, v98 row_ror:2 row_mask:0xf bank_mask:0xf
	ds_read_b128 v[14:17], v74 offset:3840
	ds_read_b128 v[18:21], v74 offset:4096
	v_add_f32_dpp v98, v98, v98 row_ror:1 row_mask:0xf bank_mask:0xf
	v_pk_fma_f32 v[60:61], v[98:99], v[84:85], v[100:101] op_sel_hi:[0,1,1]
	v_pk_fma_f32 v[62:63], v[98:99], v[86:87], v[208:209] op_sel_hi:[0,1,1]
	ds_read_b32 v210, v73 offset:3072
	v_pk_mul_f32 v[100:101], v[60:61], v[92:93]
	v_pk_fma_f32 v[100:101], v[62:63], v[94:95], v[100:101]
	s_nop 0
	v_add_f32_e32 v102, v100, v101
	ds_write_b32 v72, v102 offset:2048
	s_waitcnt lgkmcnt(8)
	v_pk_mul_f32 v[98:99], v[60:61], v[212:213]
	v_pk_fma_f32 v[98:99], v[62:63], v[214:215], v[98:99]
	v_pk_mul_f32 v[100:101], v[60:61], v[216:217]
	v_add_f32_e32 v98, v98, v99
	v_pk_mul_f32 v[208:209], v[62:63], v[218:219]
	v_pk_fma_f32 v[100:101], v[232:233], v[224:225], v[100:101] op_sel_hi:[0,1,1]
	v_add_f32_dpp v98, v98, v98 row_ror:8 row_mask:0xf bank_mask:0xf
	v_pk_fma_f32 v[208:209], v[232:233], v[226:227], v[208:209] op_sel_hi:[0,1,1]
	ds_read_b128 v[76:79], v74 offset:4608
	v_add_f32_dpp v98, v98, v98 row_ror:4 row_mask:0xf bank_mask:0xf
	ds_read_b128 v[80:83], v74 offset:4864
	ds_read_b128 v[84:87], v74 offset:5120
	v_add_f32_dpp v98, v98, v98 row_ror:2 row_mask:0xf bank_mask:0xf
	ds_read_b128 v[88:91], v74 offset:5376
	ds_read_b128 v[92:95], v74 offset:5632
	v_add_f32_dpp v98, v98, v98 row_ror:1 row_mask:0xf bank_mask:0xf
	v_pk_fma_f32 v[60:61], v[98:99], v[220:221], v[100:101] op_sel_hi:[0,1,1]
	v_pk_fma_f32 v[62:63], v[98:99], v[222:223], v[208:209] op_sel_hi:[0,1,1]
	ds_read_b32 v96, v73 offset:4608
	v_pk_mul_f32 v[100:101], v[60:61], v[228:229]
	v_pk_fma_f32 v[100:101], v[62:63], v[230:231], v[100:101]
	s_nop 0
	v_add_f32_e32 v102, v100, v101
	ds_write_b32 v72, v102 offset:4096
	s_waitcnt lgkmcnt(8)
	v_pk_mul_f32 v[98:99], v[60:61], v[2:3]
	v_pk_fma_f32 v[98:99], v[62:63], v[4:5], v[98:99]
	v_pk_mul_f32 v[100:101], v[60:61], v[6:7]
	v_add_f32_e32 v98, v98, v99
	v_pk_mul_f32 v[208:209], v[62:63], v[8:9]
	v_pk_fma_f32 v[100:101], v[210:211], v[14:15], v[100:101] op_sel_hi:[0,1,1]
	v_add_f32_dpp v98, v98, v98 row_ror:8 row_mask:0xf bank_mask:0xf
	v_pk_fma_f32 v[208:209], v[210:211], v[16:17], v[208:209] op_sel_hi:[0,1,1]
	ds_read_b128 v[212:215], v74 offset:6144
	v_add_f32_dpp v98, v98, v98 row_ror:4 row_mask:0xf bank_mask:0xf
	ds_read_b128 v[216:219], v74 offset:6400
	ds_read_b128 v[220:223], v74 offset:6656
	v_add_f32_dpp v98, v98, v98 row_ror:2 row_mask:0xf bank_mask:0xf
	ds_read_b128 v[224:227], v74 offset:6912
	ds_read_b128 v[228:231], v74 offset:7168
	v_add_f32_dpp v98, v98, v98 row_ror:1 row_mask:0xf bank_mask:0xf
	v_pk_fma_f32 v[60:61], v[98:99], v[10:11], v[100:101] op_sel_hi:[0,1,1]
	v_pk_fma_f32 v[62:63], v[98:99], v[12:13], v[208:209] op_sel_hi:[0,1,1]
	ds_read_b32 v232, v73 offset:6144
	v_pk_mul_f32 v[100:101], v[60:61], v[18:19]
	v_pk_fma_f32 v[100:101], v[62:63], v[20:21], v[100:101]
	s_nop 0
	v_add_f32_e32 v102, v100, v101
	ds_write_b32 v72, v102 offset:6144
	s_cmpk_gt_u32 s22, 0x3fd
	s_cbranch_scc1 .Liss_skip
	s_add_i32 s80, s22, 2
	s_lshl_b32 s80, s80, 4
	v_lshl_add_u64 v[242:243], v[34:35], 0, s[80:81]
	v_mov_b64_e32 v[244:245], s[46:47]
	v_mad_u64_u32 v[244:245], s[6:7], v242, s90, v[244:245]
	v_mad_i32_i24 v245, v243, s90, v245
	v_lshl_add_u64 v[246:247], v[244:245], 0, v[0:1]
	global_load_dword v64, v[246:247], off
	global_load_dword v65, v[246:247], off offset:2048
	v_lshlrev_b32_e32 v246, 1, v22
	v_mov_b32_e32 v247, v1
	v_lshl_add_u64 v[244:245], v[244:245], 0, v[246:247]
	v_add_co_u32_e32 v244, vcc, s36, v244
	v_lshlrev_b64 v[242:243], 11, v[242:243]
	s_nop 0
	v_addc_co_u32_e32 v245, vcc, 0, v245, vcc
	global_load_ushort v66, v[244:245], off
	v_or_b32_e32 v244, v242, v0
	v_mov_b32_e32 v245, v243
	v_lshl_add_u64 v[246:247], s[62:63], 0, v[244:245]
	global_load_dword v67, v[246:247], off
	v_lshl_add_u64 v[246:247], s[64:65], 0, v[244:245]
	v_lshl_add_u64 v[244:245], s[66:67], 0, v[244:245]
	v_lshl_add_u64 v[242:243], v[38:39], 0, v[242:243]
	global_load_dword v68, v[246:247], off
	global_load_dword v69, v[244:245], off
	global_load_ushort v70, v[242:243], off
; #define SCAN_LOAD(R, TOKP) do { const float* _p = (TOKP); \
;     R##nk = *(const f32x4*)(_p + opoff); R##w = *(const f32x4*)(_p + 64 + opoff); R##b = *(const f32x4*)(_p + 128 + opoff); \
;     R##k = *(const f32x4*)(_p + 192 + opoff); R##r = *(const f32x4*)(_p + 256 + opoff); R##v = _p[voff]; } while (0)
; __device__ __forceinline__ void scan_block(const int WV, const Params& P, int layer, int bh, int hv) {
;     ...
;   for (int chunk = 0; chunk < NCH; ++chunk) {
;     const int buf = chunk & 1;
;     if (chunk + 1 < NCH) { commit(buf ^ 1); Lg1 = Lgn; }
;     if (chunk + 2 < NCH) {
;       if (!prep_all_done && ((chunk + 2) >> 1) >= next_check) {
;         if (__hip_atomic_load((const gu32*)pdone_s, __ATOMIC_RELAXED, __HIP_MEMORY_SCOPE_AGENT) >= gridDim.x - 64) {
;           __builtin_amdgcn_fence(__ATOMIC_ACQUIRE, "agent");
;           prep_all_done = true;
;         } else {
;           const int t0w = (chunk + 2) >> 1;
;           wait_flags16(tflag + t0w, min(64, 512 - t0w), lane);
;           next_check = t0w + 64;
;         }
;       }
;       issue(chunk + 2);
;     }
;     if (chunk >= 1) prefetch_partner(chunk - 1);
;     {
;       const float* base = ring + (size_t)buf * SCH * 384;
;       float* yb = ypart + (size_t)buf * (SCH * 512) + yoff;
;       f32x4 Ank, Aw, Ab, Ak, Ar, Bnk, Bw, Bb, Bk, Br; float Av, Bv;
;       SCAN_LOAD(A, base);
; #pragma unroll 2
;       for (int tok = 0; tok < SCH; tok += 2) {
;         SCAN_LOAD(B, base + (tok + 1) * 384);
;         SCAN_STEP(A, yb + tok * 512);
;         SCAN_LOAD(A, base + ((tok + 2) & (SCH - 1)) * 384);
;         SCAN_STEP(B, yb + (tok + 1) * 512);
;       }
.Liss_skip:
	s_waitcnt lgkmcnt(8)
	v_pk_mul_f32 v[98:99], v[60:61], v[76:77]
	v_pk_fma_f32 v[98:99], v[62:63], v[78:79], v[98:99]
	v_pk_mul_f32 v[100:101], v[60:61], v[80:81]
	v_add_f32_e32 v98, v98, v99
	v_pk_mul_f32 v[208:209], v[62:63], v[82:83]
	v_pk_fma_f32 v[100:101], v[96:97], v[88:89], v[100:101] op_sel_hi:[0,1,1]
	v_add_f32_dpp v98, v98, v98 row_ror:8 row_mask:0xf bank_mask:0xf
	v_pk_fma_f32 v[208:209], v[96:97], v[90:91], v[208:209] op_sel_hi:[0,1,1]
	ds_read_b128 v[2:5], v74 offset:7680
	v_add_f32_dpp v98, v98, v98 row_ror:4 row_mask:0xf bank_mask:0xf
	ds_read_b128 v[6:9], v74 offset:7936
	ds_read_b128 v[10:13], v74 offset:8192
	v_add_f32_dpp v98, v98, v98 row_ror:2 row_mask:0xf bank_mask:0xf
	ds_read_b128 v[14:17], v74 offset:8448
	ds_read_b128 v[18:21], v74 offset:8704
	v_add_f32_dpp v98, v98, v98 row_ror:1 row_mask:0xf bank_mask:0xf
	v_pk_fma_f32 v[60:61], v[98:99], v[84:85], v[100:101] op_sel_hi:[0,1,1]
	v_pk_fma_f32 v[62:63], v[98:99], v[86:87], v[208:209] op_sel_hi:[0,1,1]
	ds_read_b32 v210, v73 offset:7680
	v_pk_mul_f32 v[100:101], v[60:61], v[92:93]
	v_pk_fma_f32 v[100:101], v[62:63], v[94:95], v[100:101]
	s_nop 0
	v_add_f32_e32 v102, v100, v101
	ds_write_b32 v72, v102 offset:8192
	s_waitcnt lgkmcnt(8)
	v_pk_mul_f32 v[98:99], v[60:61], v[212:213]
	v_pk_fma_f32 v[98:99], v[62:63], v[214:215], v[98:99]
	v_pk_mul_f32 v[100:101], v[60:61], v[216:217]
	v_add_f32_e32 v98, v98, v99
	v_pk_mul_f32 v[208:209], v[62:63], v[218:219]
	v_pk_fma_f32 v[100:101], v[232:233], v[224:225], v[100:101] op_sel_hi:[0,1,1]
	v_add_f32_dpp v98, v98, v98 row_ror:8 row_mask:0xf bank_mask:0xf
	v_pk_fma_f32 v[208:209], v[232:233], v[226:227], v[208:209] op_sel_hi:[0,1,1]
	ds_read_b128 v[76:79], v74 offset:9216
	v_add_f32_dpp v98, v98, v98 row_ror:4 row_mask:0xf bank_mask:0xf
	ds_read_b128 v[80:83], v74 offset:9472
	ds_read_b128 v[84:87], v74 offset:9728
	v_add_f32_dpp v98, v98, v98 row_ror:2 row_mask:0xf bank_mask:0xf
	ds_read_b128 v[88:91], v74 offset:9984
	ds_read_b128 v[92:95], v74 offset:10240
	v_add_f32_dpp v98, v98, v98 row_ror:1 row_mask:0xf bank_mask:0xf
	v_pk_fma_f32 v[60:61], v[98:99], v[220:221], v[100:101] op_sel_hi:[0,1,1]
	v_pk_fma_f32 v[62:63], v[98:99], v[222:223], v[208:209] op_sel_hi:[0,1,1]
	ds_read_b32 v96, v73 offset:9216
	v_pk_mul_f32 v[100:101], v[60:61], v[228:229]
	v_pk_fma_f32 v[100:101], v[62:63], v[230:231], v[100:101]
	s_nop 0
	v_add_f32_e32 v102, v100, v101
	ds_write_b32 v72, v102 offset:10240
	s_waitcnt lgkmcnt(8)
	v_pk_mul_f32 v[98:99], v[60:61], v[2:3]
	v_pk_fma_f32 v[98:99], v[62:63], v[4:5], v[98:99]
	v_pk_mul_f32 v[100:101], v[60:61], v[6:7]
	v_add_f32_e32 v98, v98, v99
	v_pk_mul_f32 v[208:209], v[62:63], v[8:9]
	v_pk_fma_f32 v[100:101], v[210:211], v[14:15], v[100:101] op_sel_hi:[0,1,1]
	v_add_f32_dpp v98, v98, v98 row_ror:8 row_mask:0xf bank_mask:0xf
	v_pk_fma_f32 v[208:209], v[210:211], v[16:17], v[208:209] op_sel_hi:[0,1,1]
	ds_read_b128 v[212:215], v74 offset:10752
	v_add_f32_dpp v98, v98, v98 row_ror:4 row_mask:0xf bank_mask:0xf
	ds_read_b128 v[216:219], v74 offset:11008
	ds_read_b128 v[220:223], v74 offset:11264
	v_add_f32_dpp v98, v98, v98 row_ror:2 row_mask:0xf bank_mask:0xf
	ds_read_b128 v[224:227], v74 offset:11520
	ds_read_b128 v[228:231], v74 offset:11776
	v_add_f32_dpp v98, v98, v98 row_ror:1 row_mask:0xf bank_mask:0xf
	v_pk_fma_f32 v[60:61], v[98:99], v[10:11], v[100:101] op_sel_hi:[0,1,1]
	v_pk_fma_f32 v[62:63], v[98:99], v[12:13], v[208:209] op_sel_hi:[0,1,1]
	ds_read_b32 v232, v73 offset:10752
	v_pk_mul_f32 v[100:101], v[60:61], v[18:19]
	v_pk_fma_f32 v[100:101], v[62:63], v[20:21], v[100:101]
	s_nop 0
	v_add_f32_e32 v102, v100, v101
	ds_write_b32 v72, v102 offset:12288
	s_waitcnt lgkmcnt(8)
	v_pk_mul_f32 v[98:99], v[60:61], v[76:77]
	v_pk_fma_f32 v[98:99], v[62:63], v[78:79], v[98:99]
	v_pk_mul_f32 v[100:101], v[60:61], v[80:81]
	v_add_f32_e32 v98, v98, v99
	v_pk_mul_f32 v[208:209], v[62:63], v[82:83]
	v_pk_fma_f32 v[100:101], v[96:97], v[88:89], v[100:101] op_sel_hi:[0,1,1]
	v_add_f32_dpp v98, v98, v98 row_ror:8 row_mask:0xf bank_mask:0xf
	v_pk_fma_f32 v[208:209], v[96:97], v[90:91], v[208:209] op_sel_hi:[0,1,1]
	ds_read_b128 v[2:5], v74 offset:12288
	v_add_f32_dpp v98, v98, v98 row_ror:4 row_mask:0xf bank_mask:0xf
	ds_read_b128 v[6:9], v74 offset:12544
	ds_read_b128 v[10:13], v74 offset:12800
	v_add_f32_dpp v98, v98, v98 row_ror:2 row_mask:0xf bank_mask:0xf
	ds_read_b128 v[14:17], v74 offset:13056
	ds_read_b128 v[18:21], v74 offset:13312
	v_add_f32_dpp v98, v98, v98 row_ror:1 row_mask:0xf bank_mask:0xf
	v_pk_fma_f32 v[60:61], v[98:99], v[84:85], v[100:101] op_sel_hi:[0,1,1]
	v_pk_fma_f32 v[62:63], v[98:99], v[86:87], v[208:209] op_sel_hi:[0,1,1]
	ds_read_b32 v210, v73 offset:12288
	v_pk_mul_f32 v[100:101], v[60:61], v[92:93]
	v_pk_fma_f32 v[100:101], v[62:63], v[94:95], v[100:101]
	s_nop 0
	v_add_f32_e32 v102, v100, v101
	ds_write_b32 v72, v102 offset:14336
	s_waitcnt lgkmcnt(8)
	v_pk_mul_f32 v[98:99], v[60:61], v[212:213]
	v_pk_fma_f32 v[98:99], v[62:63], v[214:215], v[98:99]
	v_pk_mul_f32 v[100:101], v[60:61], v[216:217]
	v_add_f32_e32 v98, v98, v99
	v_pk_mul_f32 v[208:209], v[62:63], v[218:219]
	v_pk_fma_f32 v[100:101], v[232:233], v[224:225], v[100:101] op_sel_hi:[0,1,1]
	v_add_f32_dpp v98, v98, v98 row_ror:8 row_mask:0xf bank_mask:0xf
	v_pk_fma_f32 v[208:209], v[232:233], v[226:227], v[208:209] op_sel_hi:[0,1,1]
	ds_read_b128 v[76:79], v74 offset:13824
	v_add_f32_dpp v98, v98, v98 row_ror:4 row_mask:0xf bank_mask:0xf
	ds_read_b128 v[80:83], v74 offset:14080
	ds_read_b128 v[84:87], v74 offset:14336
	v_add_f32_dpp v98, v98, v98 row_ror:2 row_mask:0xf bank_mask:0xf
	ds_read_b128 v[88:91], v74 offset:14592
	ds_read_b128 v[92:95], v74 offset:14848
	v_add_f32_dpp v98, v98, v98 row_ror:1 row_mask:0xf bank_mask:0xf
	v_pk_fma_f32 v[60:61], v[98:99], v[220:221], v[100:101] op_sel_hi:[0,1,1]
	v_pk_fma_f32 v[62:63], v[98:99], v[222:223], v[208:209] op_sel_hi:[0,1,1]
	ds_read_b32 v96, v73 offset:13824
	v_pk_mul_f32 v[100:101], v[60:61], v[228:229]
	v_pk_fma_f32 v[100:101], v[62:63], v[230:231], v[100:101]
	s_nop 0
	v_add_f32_e32 v102, v100, v101
	ds_write_b32 v72, v102 offset:16384
	s_waitcnt lgkmcnt(8)
; #define SCAN_LOAD(R, TOKP) do { const float* _p = (TOKP); \
;     R##nk = *(const f32x4*)(_p + opoff); R##w = *(const f32x4*)(_p + 64 + opoff); R##b = *(const f32x4*)(_p + 128 + opoff); \
;     R##k = *(const f32x4*)(_p + 192 + opoff); R##r = *(const f32x4*)(_p + 256 + opoff); R##v = _p[voff]; } while (0)
; __device__ __forceinline__ void scan_block(const int WV, const Params& P, int layer, int bh, int hv) {
;     ...
;   auto prefetch_partner = [&](int chunk) {
;     const int slot = (chunk & 1) * (SCH * 2);
;     pg1 = __hip_atomic_load(xpart + slot, __ATOMIC_RELAXED, __HIP_MEMORY_SCOPE_AGENT);
;     pg2 = __hip_atomic_load(xpart + slot + 1, __ATOMIC_RELAXED, __HIP_MEMORY_SCOPE_AGENT);
;   };
;     ...
;   for (int chunk = 0; chunk < NCH; ++chunk) {
;     const int buf = chunk & 1;
;     if (chunk + 1 < NCH) { commit(buf ^ 1); Lg1 = Lgn; }
;     if (chunk + 2 < NCH) {
;       if (!prep_all_done && ((chunk + 2) >> 1) >= next_check) {
;         if (__hip_atomic_load((const gu32*)pdone_s, __ATOMIC_RELAXED, __HIP_MEMORY_SCOPE_AGENT) >= gridDim.x - 64) {
;           __builtin_amdgcn_fence(__ATOMIC_ACQUIRE, "agent");
;           prep_all_done = true;
;         } else {
;           const int t0w = (chunk + 2) >> 1;
;           wait_flags16(tflag + t0w, min(64, 512 - t0w), lane);
;           next_check = t0w + 64;
;         }
;       }
;       issue(chunk + 2);
;     }
;     if (chunk >= 1) prefetch_partner(chunk - 1);
;     {
;       const float* base = ring + (size_t)buf * SCH * 384;
;       float* yb = ypart + (size_t)buf * (SCH * 512) + yoff;
;       f32x4 Ank, Aw, Ab, Ak, Ar, Bnk, Bw, Bb, Bk, Br; float Av, Bv;
;       SCAN_LOAD(A, base);
; #pragma unroll 2
;       for (int tok = 0; tok < SCH; tok += 2) {
;         SCAN_LOAD(B, base + (tok + 1) * 384);
;         SCAN_STEP(A, yb + tok * 512);
;         SCAN_LOAD(A, base + ((tok + 2) & (SCH - 1)) * 384);
;         SCAN_STEP(B, yb + (tok + 1) * 512);
;       }
	v_pk_mul_f32 v[98:99], v[60:61], v[2:3]
	v_pk_fma_f32 v[98:99], v[62:63], v[4:5], v[98:99]
	v_pk_mul_f32 v[100:101], v[60:61], v[6:7]
	v_add_f32_e32 v98, v98, v99
	v_pk_mul_f32 v[208:209], v[62:63], v[8:9]
	v_pk_fma_f32 v[100:101], v[210:211], v[14:15], v[100:101] op_sel_hi:[0,1,1]
	v_add_f32_dpp v98, v98, v98 row_ror:8 row_mask:0xf bank_mask:0xf
	v_pk_fma_f32 v[208:209], v[210:211], v[16:17], v[208:209] op_sel_hi:[0,1,1]
	ds_read_b128 v[212:215], v74 offset:15360
	v_add_f32_dpp v98, v98, v98 row_ror:4 row_mask:0xf bank_mask:0xf
	ds_read_b128 v[216:219], v74 offset:15616
	ds_read_b128 v[220:223], v74 offset:15872
	v_add_f32_dpp v98, v98, v98 row_ror:2 row_mask:0xf bank_mask:0xf
	ds_read_b128 v[224:227], v74 offset:16128
	ds_read_b128 v[228:231], v74 offset:16384
	v_add_f32_dpp v98, v98, v98 row_ror:1 row_mask:0xf bank_mask:0xf
	v_pk_fma_f32 v[60:61], v[98:99], v[10:11], v[100:101] op_sel_hi:[0,1,1]
	v_pk_fma_f32 v[62:63], v[98:99], v[12:13], v[208:209] op_sel_hi:[0,1,1]
	ds_read_b32 v232, v73 offset:15360
	v_pk_mul_f32 v[100:101], v[60:61], v[18:19]
	v_pk_fma_f32 v[100:101], v[62:63], v[20:21], v[100:101]
	s_nop 0
	v_add_f32_e32 v102, v100, v101
	ds_write_b32 v72, v102 offset:18432
	s_waitcnt lgkmcnt(8)
	v_pk_mul_f32 v[98:99], v[60:61], v[76:77]
	v_pk_fma_f32 v[98:99], v[62:63], v[78:79], v[98:99]
	v_pk_mul_f32 v[100:101], v[60:61], v[80:81]
	v_add_f32_e32 v98, v98, v99
	v_pk_mul_f32 v[208:209], v[62:63], v[82:83]
	v_pk_fma_f32 v[100:101], v[96:97], v[88:89], v[100:101] op_sel_hi:[0,1,1]
	v_add_f32_dpp v98, v98, v98 row_ror:8 row_mask:0xf bank_mask:0xf
	v_pk_fma_f32 v[208:209], v[96:97], v[90:91], v[208:209] op_sel_hi:[0,1,1]
	ds_read_b128 v[2:5], v74 offset:16896
	v_add_f32_dpp v98, v98, v98 row_ror:4 row_mask:0xf bank_mask:0xf
	ds_read_b128 v[6:9], v74 offset:17152
	ds_read_b128 v[10:13], v74 offset:17408
	v_add_f32_dpp v98, v98, v98 row_ror:2 row_mask:0xf bank_mask:0xf
	ds_read_b128 v[14:17], v74 offset:17664
	ds_read_b128 v[18:21], v74 offset:17920
	v_add_f32_dpp v98, v98, v98 row_ror:1 row_mask:0xf bank_mask:0xf
	v_pk_fma_f32 v[60:61], v[98:99], v[84:85], v[100:101] op_sel_hi:[0,1,1]
	v_pk_fma_f32 v[62:63], v[98:99], v[86:87], v[208:209] op_sel_hi:[0,1,1]
	ds_read_b32 v210, v73 offset:16896
	v_pk_mul_f32 v[100:101], v[60:61], v[92:93]
	v_pk_fma_f32 v[100:101], v[62:63], v[94:95], v[100:101]
	s_nop 0
	v_add_f32_e32 v102, v100, v101
	ds_write_b32 v72, v102 offset:20480
	s_waitcnt lgkmcnt(8)
	v_pk_mul_f32 v[98:99], v[60:61], v[212:213]
	v_pk_fma_f32 v[98:99], v[62:63], v[214:215], v[98:99]
	v_pk_mul_f32 v[100:101], v[60:61], v[216:217]
	v_add_f32_e32 v98, v98, v99
	v_pk_mul_f32 v[208:209], v[62:63], v[218:219]
	v_pk_fma_f32 v[100:101], v[232:233], v[224:225], v[100:101] op_sel_hi:[0,1,1]
	v_add_f32_dpp v98, v98, v98 row_ror:8 row_mask:0xf bank_mask:0xf
	v_pk_fma_f32 v[208:209], v[232:233], v[226:227], v[208:209] op_sel_hi:[0,1,1]
	ds_read_b128 v[76:79], v74 offset:18432
	v_add_f32_dpp v98, v98, v98 row_ror:4 row_mask:0xf bank_mask:0xf
	ds_read_b128 v[80:83], v74 offset:18688
	ds_read_b128 v[84:87], v74 offset:18944
	v_add_f32_dpp v98, v98, v98 row_ror:2 row_mask:0xf bank_mask:0xf
	ds_read_b128 v[88:91], v74 offset:19200
	ds_read_b128 v[92:95], v74 offset:19456
	v_add_f32_dpp v98, v98, v98 row_ror:1 row_mask:0xf bank_mask:0xf
	v_pk_fma_f32 v[60:61], v[98:99], v[220:221], v[100:101] op_sel_hi:[0,1,1]
	v_pk_fma_f32 v[62:63], v[98:99], v[222:223], v[208:209] op_sel_hi:[0,1,1]
	ds_read_b32 v96, v73 offset:18432
	v_pk_mul_f32 v[100:101], v[60:61], v[228:229]
	v_pk_fma_f32 v[100:101], v[62:63], v[230:231], v[100:101]
	s_nop 0
	v_add_f32_e32 v102, v100, v101
	ds_write_b32 v72, v102 offset:22528
	global_load_dwordx2 v[42:43], v[254:255], off sc1
	global_load_dwordx2 v[44:45], v[254:255], off offset:8 sc1
	s_waitcnt lgkmcnt(8)
; #define LDS_BARRIER() do { asm volatile("s_waitcnt lgkmcnt(0)" ::: "memory"); __builtin_amdgcn_s_barrier(); asm volatile("" ::: "memory"); } while (0)
; #define SCAN_LOAD(R, TOKP) do { const float* _p = (TOKP); \
;     R##nk = *(const f32x4*)(_p + opoff); R##w = *(const f32x4*)(_p + 64 + opoff); R##b = *(const f32x4*)(_p + 128 + opoff); \
;     R##k = *(const f32x4*)(_p + 192 + opoff); R##r = *(const f32x4*)(_p + 256 + opoff); R##v = _p[voff]; } while (0)
; __device__ __forceinline__ void scan_block(const int WV, const Params& P, int layer, int bh, int hv) {
;     ...
;   for (int chunk = 0; chunk < NCH; ++chunk) {
;     const int buf = chunk & 1;
;     if (chunk + 1 < NCH) { commit(buf ^ 1); Lg1 = Lgn; }
;     if (chunk + 2 < NCH) {
;       if (!prep_all_done && ((chunk + 2) >> 1) >= next_check) {
;         if (__hip_atomic_load((const gu32*)pdone_s, __ATOMIC_RELAXED, __HIP_MEMORY_SCOPE_AGENT) >= gridDim.x - 64) {
;           __builtin_amdgcn_fence(__ATOMIC_ACQUIRE, "agent");
;           prep_all_done = true;
;         } else {
;           const int t0w = (chunk + 2) >> 1;
;           wait_flags16(tflag + t0w, min(64, 512 - t0w), lane);
;           next_check = t0w + 64;
;         }
;       }
;       issue(chunk + 2);
;     }
;     if (chunk >= 1) prefetch_partner(chunk - 1);
;     {
;       const float* base = ring + (size_t)buf * SCH * 384;
;       float* yb = ypart + (size_t)buf * (SCH * 512) + yoff;
;       f32x4 Ank, Aw, Ab, Ak, Ar, Bnk, Bw, Bb, Bk, Br; float Av, Bv;
;       SCAN_LOAD(A, base);
; #pragma unroll 2
;       for (int tok = 0; tok < SCH; tok += 2) {
;         SCAN_LOAD(B, base + (tok + 1) * 384);
;         SCAN_STEP(A, yb + tok * 512);
;         SCAN_LOAD(A, base + ((tok + 2) & (SCH - 1)) * 384);
;         SCAN_STEP(B, yb + (tok + 1) * 512);
;       }
;     }
;     LDS_BARRIER();
;     if (chunk >= 1) post_b(chunk - 1, (unsigned)(layer * 2048 + chunk));
	v_pk_mul_f32 v[98:99], v[60:61], v[2:3]
	v_pk_fma_f32 v[98:99], v[62:63], v[4:5], v[98:99]
	v_pk_mul_f32 v[100:101], v[60:61], v[6:7]
	v_add_f32_e32 v98, v98, v99
	v_pk_mul_f32 v[208:209], v[62:63], v[8:9]
	v_pk_fma_f32 v[100:101], v[210:211], v[14:15], v[100:101] op_sel_hi:[0,1,1]
	v_add_f32_dpp v98, v98, v98 row_ror:8 row_mask:0xf bank_mask:0xf
	v_pk_fma_f32 v[208:209], v[210:211], v[16:17], v[208:209] op_sel_hi:[0,1,1]
	ds_read_b128 v[212:215], v74 offset:19968
	v_add_f32_dpp v98, v98, v98 row_ror:4 row_mask:0xf bank_mask:0xf
	ds_read_b128 v[216:219], v74 offset:20224
	ds_read_b128 v[220:223], v74 offset:20480
	v_add_f32_dpp v98, v98, v98 row_ror:2 row_mask:0xf bank_mask:0xf
	ds_read_b128 v[224:227], v74 offset:20736
	ds_read_b128 v[228:231], v74 offset:20992
	v_add_f32_dpp v98, v98, v98 row_ror:1 row_mask:0xf bank_mask:0xf
	v_pk_fma_f32 v[60:61], v[98:99], v[10:11], v[100:101] op_sel_hi:[0,1,1]
	v_pk_fma_f32 v[62:63], v[98:99], v[12:13], v[208:209] op_sel_hi:[0,1,1]
	ds_read_b32 v232, v73 offset:19968
	v_pk_mul_f32 v[100:101], v[60:61], v[18:19]
	v_pk_fma_f32 v[100:101], v[62:63], v[20:21], v[100:101]
	s_nop 0
	v_add_f32_e32 v102, v100, v101
	ds_write_b32 v72, v102 offset:24576
	s_waitcnt lgkmcnt(8)
	v_pk_mul_f32 v[98:99], v[60:61], v[76:77]
	v_pk_fma_f32 v[98:99], v[62:63], v[78:79], v[98:99]
	v_pk_mul_f32 v[100:101], v[60:61], v[80:81]
	v_add_f32_e32 v98, v98, v99
	v_pk_mul_f32 v[208:209], v[62:63], v[82:83]
	v_pk_fma_f32 v[100:101], v[96:97], v[88:89], v[100:101] op_sel_hi:[0,1,1]
	v_add_f32_dpp v98, v98, v98 row_ror:8 row_mask:0xf bank_mask:0xf
	v_pk_fma_f32 v[208:209], v[96:97], v[90:91], v[208:209] op_sel_hi:[0,1,1]
	ds_read_b128 v[2:5], v74 offset:21504
	v_add_f32_dpp v98, v98, v98 row_ror:4 row_mask:0xf bank_mask:0xf
	ds_read_b128 v[6:9], v74 offset:21760
	ds_read_b128 v[10:13], v74 offset:22016
	v_add_f32_dpp v98, v98, v98 row_ror:2 row_mask:0xf bank_mask:0xf
	ds_read_b128 v[14:17], v74 offset:22272
	ds_read_b128 v[18:21], v74 offset:22528
	v_add_f32_dpp v98, v98, v98 row_ror:1 row_mask:0xf bank_mask:0xf
	v_pk_fma_f32 v[60:61], v[98:99], v[84:85], v[100:101] op_sel_hi:[0,1,1]
	v_pk_fma_f32 v[62:63], v[98:99], v[86:87], v[208:209] op_sel_hi:[0,1,1]
	ds_read_b32 v210, v73 offset:21504
	v_pk_mul_f32 v[100:101], v[60:61], v[92:93]
	v_pk_fma_f32 v[100:101], v[62:63], v[94:95], v[100:101]
	s_nop 0
	v_add_f32_e32 v102, v100, v101
	ds_write_b32 v72, v102 offset:26624
	s_waitcnt lgkmcnt(8)
	v_pk_mul_f32 v[98:99], v[60:61], v[212:213]
	v_pk_fma_f32 v[98:99], v[62:63], v[214:215], v[98:99]
	v_pk_mul_f32 v[100:101], v[60:61], v[216:217]
	v_add_f32_e32 v98, v98, v99
	v_pk_mul_f32 v[208:209], v[62:63], v[218:219]
	v_pk_fma_f32 v[100:101], v[232:233], v[224:225], v[100:101] op_sel_hi:[0,1,1]
	v_add_f32_dpp v98, v98, v98 row_ror:8 row_mask:0xf bank_mask:0xf
	v_pk_fma_f32 v[208:209], v[232:233], v[226:227], v[208:209] op_sel_hi:[0,1,1]
	s_nop 0
	v_add_f32_dpp v98, v98, v98 row_ror:4 row_mask:0xf bank_mask:0xf
	s_nop 1
	v_add_f32_dpp v98, v98, v98 row_ror:2 row_mask:0xf bank_mask:0xf
	s_nop 1
	v_add_f32_dpp v98, v98, v98 row_ror:1 row_mask:0xf bank_mask:0xf
	v_pk_fma_f32 v[60:61], v[98:99], v[220:221], v[100:101] op_sel_hi:[0,1,1]
	v_pk_fma_f32 v[62:63], v[98:99], v[222:223], v[208:209] op_sel_hi:[0,1,1]
	v_pk_mul_f32 v[100:101], v[60:61], v[228:229]
	v_pk_fma_f32 v[100:101], v[62:63], v[230:231], v[100:101]
	s_nop 0
	v_add_f32_e32 v102, v100, v101
	ds_write_b32 v72, v102 offset:28672
	s_waitcnt lgkmcnt(2)
	v_pk_mul_f32 v[98:99], v[60:61], v[2:3]
	v_pk_fma_f32 v[98:99], v[62:63], v[4:5], v[98:99]
	v_pk_mul_f32 v[100:101], v[60:61], v[6:7]
	v_add_f32_e32 v98, v98, v99
	v_pk_mul_f32 v[208:209], v[62:63], v[8:9]
	v_pk_fma_f32 v[100:101], v[210:211], v[14:15], v[100:101] op_sel_hi:[0,1,1]
	v_add_f32_dpp v98, v98, v98 row_ror:8 row_mask:0xf bank_mask:0xf
	v_pk_fma_f32 v[208:209], v[210:211], v[16:17], v[208:209] op_sel_hi:[0,1,1]
	s_nop 0
	v_add_f32_dpp v98, v98, v98 row_ror:4 row_mask:0xf bank_mask:0xf
	s_nop 1
	v_add_f32_dpp v98, v98, v98 row_ror:2 row_mask:0xf bank_mask:0xf
	s_nop 1
	v_add_f32_dpp v98, v98, v98 row_ror:1 row_mask:0xf bank_mask:0xf
	v_pk_fma_f32 v[60:61], v[98:99], v[10:11], v[100:101] op_sel_hi:[0,1,1]
	v_pk_fma_f32 v[62:63], v[98:99], v[12:13], v[208:209] op_sel_hi:[0,1,1]
	v_pk_mul_f32 v[100:101], v[60:61], v[18:19]
	v_pk_fma_f32 v[100:101], v[62:63], v[20:21], v[100:101]
	s_nop 0
	v_add_f32_e32 v102, v100, v101
	ds_write_b32 v72, v102 offset:30720
	s_cmp_eq_u32 s22, 0
	s_cbranch_scc1 .Lpb_skip
	s_add_i32 s80, s22, s31
	v_mov_b32_e32 v204, s80
